# P0 row loop: wave sum and gate reduction levels via lane swaps and DPP instead of LDS bpermute round trips
# baseline (speedup 1.0000x reference)
; __device__ __forceinline__ unsigned pk2(float lo, float hi) { return cvt_pk_bf16(lo, hi); }
; __device__ __forceinline__ void phase0(const Params& P, unsigned char* smem) {
;     ...
;             float ss = 0.f;
; #pragma unroll
;             for (int j = 0; j < 16; ++j) ss += v[j] * v[j];
;             ss = wave_sum(ss);
;             const float rstd = rsqrtf(ss * (1.0f / DM) + EPS);
; #pragma unroll
;             for (int j = 0; j < 16; ++j) v[j] *= rstd * gm[j];
;             uint4 o0, o1;
;             o0.x = pk2(v[0], v[1]); o0.y = pk2(v[2], v[3]); o0.z = pk2(v[4], v[5]); o0.w = pk2(v[6], v[7]);
;             o1.x = pk2(v[8], v[9]); o1.y = pk2(v[10], v[11]); o1.z = pk2(v[12], v[13]); o1.w = pk2(v[14], v[15]);
;             *(uint4*)(hn + (size_t)r * DM + c0) = o0;
;             *(uint4*)(hn + (size_t)r * DM + c1) = o1;
;             float r8[8], r4[4], r2[2], r1;
; #pragma unroll
;             for (int i = 0; i < 8; ++i) {
;                 float dd[2];
; #pragma unroll
;                 for (int hh = 0; hh < 2; ++hh) {
;                     const float* gwc = gw + (i + 8 * hh) * 1024;
;                     const float4 w0 = *(const float4*)(gwc + c0), w1 = *(const float4*)(gwc + c0 + 4), w2 = *(const float4*)(gwc + c1), w3 = *(const float4*)(gwc + c1 + 4);
;                     dd[hh] = v[0] * w0.x + v[1] * w0.y + v[2] * w0.z + v[3] * w0.w + v[4] * w1.x + v[5] * w1.y + v[6] * w1.z + v[7] * w1.w
;                            + v[8] * w2.x + v[9] * w2.y + v[10] * w2.z + v[11] * w2.w + v[12] * w3.x + v[13] * w3.y + v[14] * w3.z + v[15] * w3.w;
.LBB0_39:
	s_or_b64 exec, exec, s[62:63]
	v_pk_mul_f32 v[58:59], v[38:39], v[38:39]
	v_pk_mul_f32 v[60:61], v[40:41], v[40:41]
	v_add_f32_e32 v53, v58, v59
	v_add_f32_e32 v53, v60, v53
	v_pk_mul_f32 v[62:63], v[46:47], v[46:47]
	v_add_f32_e32 v53, v61, v53
	v_add_f32_e32 v53, v62, v53
	v_pk_mul_f32 v[76:77], v[48:49], v[48:49]
	v_add_f32_e32 v53, v63, v53
	v_add_f32_e32 v53, v76, v53
	v_pk_mul_f32 v[78:79], v[42:43], v[42:43]
	v_add_f32_e32 v53, v77, v53
	v_add_f32_e32 v53, v78, v53
	v_pk_mul_f32 v[80:81], v[44:45], v[44:45]
	v_add_f32_e32 v53, v79, v53
	v_add_f32_e32 v53, v80, v53
	v_pk_mul_f32 v[82:83], v[34:35], v[34:35]
	v_add_f32_e32 v53, v81, v53
	v_add_f32_e32 v53, v82, v53
	v_pk_mul_f32 v[84:85], v[36:37], v[36:37]
	v_add_f32_e32 v53, v83, v53
	v_add_f32_e32 v53, v84, v53
	v_add_f32_e32 v53, v85, v53
	v_mov_b32_e32 v58, v53
	s_and_b64 s[12:13], exec, s[12:13]
	s_or_b64 s[34:35], s[12:13], s[34:35]
	s_waitcnt lgkmcnt(0)
	v_permlane32_swap_b32_e32 v53, v58
	v_add_f32_e32 v53, v53, v58
	v_mov_b32_e32 v58, v53
	s_nop 1
	v_permlane16_swap_b32_e32 v53, v58
	v_add_f32_e32 v53, v53, v58
	s_nop 1
	v_add_f32_dpp v53, v53, v53 row_ror:8 row_mask:0xf bank_mask:0xf
	s_nop 1
	v_add_f32_dpp v53, v53, v53 row_ror:4 row_mask:0xf bank_mask:0xf
	s_nop 1
	v_add_f32_dpp v53, v53, v53 quad_perm:[2,3,0,1] row_mask:0xf bank_mask:0xf
	s_nop 1
	v_add_f32_dpp v53, v53, v53 quad_perm:[1,0,3,2] row_mask:0xf bank_mask:0xf
	v_fmamk_f32 v53, v53, 0x3a800000, v66
	v_mul_f32_e32 v58, 0x4b800000, v53
	v_cmp_gt_f32_e64 s[12:13], s68, v53
	s_nop 1
	v_cndmask_b32_e64 v53, v53, v58, s[12:13]
	v_rsq_f32_e32 v53, v53
	s_nop 0
	v_mul_f32_e32 v58, 0x45800000, v53
	v_cndmask_b32_e64 v58, v53, v58, s[12:13]
	v_pk_mul_f32 v[60:61], v[6:7], v[58:59] op_sel_hi:[1,0]
	v_pk_mul_f32 v[76:77], v[8:9], v[58:59] op_sel_hi:[1,0]
	v_pk_mul_f32 v[84:85], v[16:17], v[58:59] op_sel_hi:[1,0]
	v_pk_mul_f32 v[86:87], v[10:11], v[58:59] op_sel_hi:[1,0]
	v_pk_mul_f32 v[62:63], v[38:39], v[60:61]
	v_pk_mul_f32 v[60:61], v[40:41], v[76:77]
	v_pk_mul_f32 v[40:41], v[44:45], v[84:85]
	v_pk_mul_f32 v[38:39], v[34:35], v[86:87]
	ds_read_b128 v[84:87], v65
	v_pk_mul_f32 v[88:89], v[12:13], v[58:59] op_sel_hi:[1,0]
	v_pk_mul_f32 v[78:79], v[2:3], v[58:59] op_sel_hi:[1,0]
	v_pk_mul_f32 v[34:35], v[36:37], v[88:89]
	ds_read_b128 v[88:91], v65 offset:16
	ds_read_b128 v[92:95], v65 offset:2048
	ds_read_b128 v[96:99], v65 offset:2064
	s_waitcnt lgkmcnt(3)
	v_mul_f32_e32 v44, v85, v63
	v_fmac_f32_e32 v44, v84, v62
	v_fmac_f32_e32 v44, v60, v86
	v_pk_mul_f32 v[80:81], v[4:5], v[58:59] op_sel_hi:[1,0]
	v_pk_mul_f32 v[82:83], v[14:15], v[58:59] op_sel_hi:[1,0]
	v_pk_mul_f32 v[58:59], v[46:47], v[78:79]
	v_fmac_f32_e32 v44, v61, v87
	s_waitcnt lgkmcnt(2)
	v_fmac_f32_e32 v44, v58, v88
	v_pk_mul_f32 v[46:47], v[48:49], v[80:81]
	v_fmac_f32_e32 v44, v59, v89
	v_fmac_f32_e32 v44, v46, v90
	v_pk_mul_f32 v[42:43], v[42:43], v[82:83]
	v_fmac_f32_e32 v44, v47, v91
	s_waitcnt lgkmcnt(1)
	v_fmac_f32_e32 v44, v42, v92
	v_fmac_f32_e32 v44, v43, v93
	ds_read_b128 v[84:87], v65 offset:32768
	v_fmac_f32_e32 v44, v40, v94
	v_fmac_f32_e32 v44, v41, v95
	s_waitcnt lgkmcnt(1)
	v_fmac_f32_e32 v44, v38, v96
	v_fmac_f32_e32 v44, v39, v97
	v_fmac_f32_e32 v44, v34, v98
	s_waitcnt lgkmcnt(0)
	v_mul_f32_e32 v45, v63, v85
	v_fmac_f32_e32 v44, v35, v99
	ds_read_b128 v[88:91], v65 offset:32784
	ds_read_b128 v[92:95], v65 offset:34816
	ds_read_b128 v[96:99], v65 offset:34832
	v_fmac_f32_e32 v45, v62, v84
	v_fmac_f32_e32 v45, v60, v86
	v_fmac_f32_e32 v45, v61, v87
	s_waitcnt lgkmcnt(2)
	v_fmac_f32_e32 v45, v58, v88
	v_fmac_f32_e32 v45, v59, v89
	v_fmac_f32_e32 v45, v46, v90
	v_fmac_f32_e32 v45, v47, v91
	s_waitcnt lgkmcnt(1)
	v_fmac_f32_e32 v45, v42, v92
	v_fmac_f32_e32 v45, v43, v93
	v_fmac_f32_e32 v45, v40, v94
	v_lshl_add_u64 v[36:37], s[28:29], 0, v[54:55]
	v_fmac_f32_e32 v45, v41, v95
	s_waitcnt lgkmcnt(0)
	v_fmac_f32_e32 v45, v38, v96
	v_add_co_u32_e64 v36, s[12:13], s69, v36
	v_cvt_pk_bf16_f32 v76, v62, v63
	v_cvt_pk_bf16_f32 v77, v60, v61
	v_cvt_pk_bf16_f32 v78, v58, v59
	v_cvt_pk_bf16_f32 v79, v46, v47
	v_fmac_f32_e32 v45, v39, v97
	v_addc_co_u32_e64 v37, s[12:13], 0, v37, s[12:13]
	v_cvt_pk_bf16_f32 v80, v42, v43
	v_cvt_pk_bf16_f32 v81, v40, v41
	v_cvt_pk_bf16_f32 v82, v38, v39
	v_cvt_pk_bf16_f32 v83, v34, v35
	v_fmac_f32_e32 v45, v34, v98
	global_store_dwordx4 v[36:37], v[76:79], off
	global_store_dwordx4 v[36:37], v[80:83], off offset:1024
	v_fmac_f32_e32 v45, v35, v99
	ds_read_b128 v[76:79], v65 offset:38928
	ds_read_b128 v[80:83], v65 offset:38912
	ds_read_b128 v[84:87], v65 offset:4112
	ds_read_b128 v[88:91], v65 offset:4096
	ds_read_b128 v[92:95], v65 offset:36880
	ds_read_b128 v[96:99], v65 offset:36864
	ds_read_b128 v[100:103], v65 offset:6160
	ds_read_b128 v[104:107], v65 offset:6144
	v_cndmask_b32_e64 v48, v44, v45, s[0:1]
	v_cndmask_b32_e64 v36, v45, v44, s[0:1]
	s_waitcnt lgkmcnt(4)
	v_mul_f32_e32 v37, v62, v88
	s_waitcnt lgkmcnt(2)
	v_mul_f32_e32 v44, v62, v96
	v_fmac_f32_e32 v37, v63, v89
	v_fmac_f32_e32 v44, v63, v97
	v_fmac_f32_e32 v37, v60, v90
	v_fmac_f32_e32 v44, v60, v98
	v_fmac_f32_e32 v37, v61, v91
	v_fmac_f32_e32 v44, v61, v99
	v_fmac_f32_e32 v37, v58, v84
	v_fmac_f32_e32 v44, v58, v92
	v_fmac_f32_e32 v37, v59, v85
	v_fmac_f32_e32 v44, v59, v93
	v_fmac_f32_e32 v37, v46, v86
	v_fmac_f32_e32 v44, v46, v94
	v_fmac_f32_e32 v37, v47, v87
	v_fmac_f32_e32 v44, v47, v95
	s_waitcnt lgkmcnt(0)
; __device__ __forceinline__ void phase0(const Params& P, unsigned char* smem) {
;     ...
; #pragma unroll
;             for (int i = 0; i < 8; ++i) {
;                 float dd[2];
; #pragma unroll
;                 for (int hh = 0; hh < 2; ++hh) {
;                     const float* gwc = gw + (i + 8 * hh) * 1024;
;                     const float4 w0 = *(const float4*)(gwc + c0), w1 = *(const float4*)(gwc + c0 + 4), w2 = *(const float4*)(gwc + c1), w3 = *(const float4*)(gwc + c1 + 4);
;                     dd[hh] = v[0] * w0.x + v[1] * w0.y + v[2] * w0.z + v[3] * w0.w + v[4] * w1.x + v[5] * w1.y + v[6] * w1.z + v[7] * w1.w
;                            + v[8] * w2.x + v[9] * w2.y + v[10] * w2.z + v[11] * w2.w + v[12] * w3.x + v[13] * w3.y + v[14] * w3.z + v[15] * w3.w;
;                 }
;                 const bool up = (lane & 32) != 0; const float keep = up ? dd[1] : dd[0], send = up ? dd[0] : dd[1];
;                 r8[i] = keep + __shfl_xor(send, 32, 64);
;                 if ((i & 3) == 3) __builtin_amdgcn_sched_barrier(0);
;             }
	v_fmac_f32_e32 v37, v42, v104
	v_fmac_f32_e32 v44, v42, v80
	v_fmac_f32_e32 v37, v43, v105
	v_fmac_f32_e32 v44, v43, v81
	v_fmac_f32_e32 v37, v40, v106
	v_fmac_f32_e32 v44, v40, v82
	v_fmac_f32_e32 v37, v41, v107
	v_fmac_f32_e32 v44, v41, v83
	v_fmac_f32_e32 v37, v38, v100
	v_fmac_f32_e32 v44, v38, v76
	ds_bpermute_b32 v48, v69, v48
	v_fmac_f32_e32 v37, v39, v101
	v_fmac_f32_e32 v44, v39, v77
	v_fmac_f32_e32 v37, v34, v102
	v_fmac_f32_e32 v44, v34, v78
	v_fmac_f32_e32 v37, v35, v103
	v_fmac_f32_e32 v44, v35, v79
	ds_read_b128 v[76:79], v65 offset:43024
	ds_read_b128 v[80:83], v65 offset:43008
	ds_read_b128 v[84:87], v65 offset:8208
	ds_read_b128 v[88:91], v65 offset:8192
	ds_read_b128 v[92:95], v65 offset:40976
	ds_read_b128 v[96:99], v65 offset:40960
	ds_read_b128 v[100:103], v65 offset:10256
	ds_read_b128 v[104:107], v65 offset:10240
	s_waitcnt lgkmcnt(8)
	v_add_f32_e32 v36, v36, v48
	v_cndmask_b32_e64 v45, v44, v37, s[0:1]
	v_cndmask_b32_e64 v37, v37, v44, s[0:1]
	s_waitcnt lgkmcnt(4)
	v_mul_f32_e32 v44, v62, v88
	s_waitcnt lgkmcnt(2)
	v_mul_f32_e32 v48, v62, v96
	v_fmac_f32_e32 v44, v63, v89
	v_fmac_f32_e32 v48, v63, v97
	v_fmac_f32_e32 v44, v60, v90
	v_fmac_f32_e32 v48, v60, v98
	v_fmac_f32_e32 v44, v61, v91
	v_fmac_f32_e32 v48, v61, v99
	v_fmac_f32_e32 v44, v58, v84
	v_fmac_f32_e32 v48, v58, v92
	v_fmac_f32_e32 v44, v59, v85
	v_fmac_f32_e32 v48, v59, v93
	v_fmac_f32_e32 v44, v46, v86
	v_fmac_f32_e32 v48, v46, v94
	v_fmac_f32_e32 v44, v47, v87
	v_fmac_f32_e32 v48, v47, v95
	s_waitcnt lgkmcnt(0)
	v_fmac_f32_e32 v44, v42, v104
	v_fmac_f32_e32 v48, v42, v80
	v_fmac_f32_e32 v44, v43, v105
	v_fmac_f32_e32 v48, v43, v81
	v_fmac_f32_e32 v44, v40, v106
	v_fmac_f32_e32 v48, v40, v82
	v_fmac_f32_e32 v44, v41, v107
	v_fmac_f32_e32 v48, v41, v83
	v_fmac_f32_e32 v44, v38, v100
	v_fmac_f32_e32 v48, v38, v76
	v_fmac_f32_e32 v44, v39, v101
	v_fmac_f32_e32 v48, v39, v77
	v_fmac_f32_e32 v44, v34, v102
	v_fmac_f32_e32 v48, v34, v78
	v_fmac_f32_e32 v44, v35, v103
	v_fmac_f32_e32 v48, v35, v79
	ds_read_b128 v[76:79], v65 offset:47120
	ds_read_b128 v[80:83], v65 offset:47104
	ds_read_b128 v[84:87], v65 offset:12304
	ds_read_b128 v[88:91], v65 offset:12288
	ds_read_b128 v[92:95], v65 offset:45072
	ds_read_b128 v[96:99], v65 offset:45056
	ds_read_b128 v[100:103], v65 offset:14352
	ds_read_b128 v[104:107], v65 offset:14336
	s_waitcnt lgkmcnt(4)
	v_mul_f32_e32 v53, v62, v88
	v_fmac_f32_e32 v53, v63, v89
	v_fmac_f32_e32 v53, v60, v90
	v_fmac_f32_e32 v53, v61, v91
	v_fmac_f32_e32 v53, v58, v84
	s_waitcnt lgkmcnt(2)
	v_mul_f32_e32 v84, v62, v96
	v_fmac_f32_e32 v84, v63, v97
	v_fmac_f32_e32 v84, v60, v98
	v_fmac_f32_e32 v84, v61, v99
	v_fmac_f32_e32 v84, v58, v92
	v_fmac_f32_e32 v53, v59, v85
	v_fmac_f32_e32 v84, v59, v93
	v_fmac_f32_e32 v53, v46, v86
	v_fmac_f32_e32 v84, v46, v94
	v_fmac_f32_e32 v53, v47, v87
	v_fmac_f32_e32 v84, v47, v95
	s_waitcnt lgkmcnt(0)
	v_fmac_f32_e32 v53, v42, v104
	v_fmac_f32_e32 v84, v42, v80
	v_fmac_f32_e32 v53, v43, v105
	v_fmac_f32_e32 v84, v43, v81
	v_fmac_f32_e32 v53, v40, v106
	v_fmac_f32_e32 v84, v40, v82
	v_fmac_f32_e32 v53, v41, v107
	v_fmac_f32_e32 v84, v41, v83
	v_fmac_f32_e32 v53, v38, v100
	v_fmac_f32_e32 v84, v38, v76
	v_fmac_f32_e32 v53, v39, v101
	v_fmac_f32_e32 v84, v39, v77
	v_fmac_f32_e32 v53, v34, v102
	v_fmac_f32_e32 v84, v34, v78
	v_fmac_f32_e32 v53, v35, v103
	v_fmac_f32_e32 v84, v35, v79
	ds_bpermute_b32 v37, v69, v37
	v_cndmask_b32_e64 v49, v44, v48, s[0:1]
	v_cndmask_b32_e64 v76, v53, v84, s[0:1]
	ds_bpermute_b32 v49, v69, v49
	ds_bpermute_b32 v76, v69, v76
	s_waitcnt lgkmcnt(2)
	v_add_f32_e32 v37, v45, v37
	v_cndmask_b32_e64 v44, v48, v44, s[0:1]
	v_cndmask_b32_e64 v45, v84, v53, s[0:1]
	s_waitcnt lgkmcnt(1)
	v_add_f32_e32 v44, v44, v49
	s_waitcnt lgkmcnt(0)
	v_add_f32_e32 v45, v45, v76
	ds_read_b128 v[76:79], v65 offset:16384
	ds_read_b128 v[80:83], v65 offset:16400
	ds_read_b128 v[84:87], v65 offset:18432
	ds_read_b128 v[88:91], v65 offset:18448
	ds_read_b128 v[92:95], v65 offset:49152
	s_waitcnt lgkmcnt(4)
	v_mul_f32_e32 v48, v63, v77
	v_fmac_f32_e32 v48, v62, v76
	v_fmac_f32_e32 v48, v60, v78
	v_fmac_f32_e32 v48, v61, v79
	s_waitcnt lgkmcnt(3)
	v_fmac_f32_e32 v48, v58, v80
	v_fmac_f32_e32 v48, v59, v81
	v_fmac_f32_e32 v48, v46, v82
	v_fmac_f32_e32 v48, v47, v83
	s_waitcnt lgkmcnt(2)
	v_fmac_f32_e32 v48, v42, v84
	v_fmac_f32_e32 v48, v43, v85
	v_fmac_f32_e32 v48, v40, v86
	s_waitcnt lgkmcnt(0)
	v_mul_f32_e32 v49, v63, v93
	v_fmac_f32_e32 v48, v41, v87
	ds_read_b128 v[76:79], v65 offset:49168
	ds_read_b128 v[80:83], v65 offset:51200
	ds_read_b128 v[84:87], v65 offset:51216
	v_fmac_f32_e32 v49, v62, v92
	v_fmac_f32_e32 v49, v60, v94
	v_fmac_f32_e32 v49, v61, v95
	s_waitcnt lgkmcnt(2)
	v_fmac_f32_e32 v49, v58, v76
	v_fmac_f32_e32 v49, v59, v77
	v_fmac_f32_e32 v49, v46, v78
	v_fmac_f32_e32 v49, v47, v79
	s_waitcnt lgkmcnt(1)
	v_fmac_f32_e32 v49, v42, v80
	v_fmac_f32_e32 v49, v43, v81
	v_fmac_f32_e32 v49, v40, v82
	v_fmac_f32_e32 v49, v41, v83
	v_fmac_f32_e32 v48, v38, v88
	s_waitcnt lgkmcnt(0)
	v_fmac_f32_e32 v49, v38, v84
	v_fmac_f32_e32 v48, v39, v89
	v_fmac_f32_e32 v49, v39, v85
	v_fmac_f32_e32 v48, v34, v90
	v_fmac_f32_e32 v49, v34, v86
	v_fmac_f32_e32 v48, v35, v91
	v_fmac_f32_e32 v49, v35, v87
	v_cndmask_b32_e64 v53, v48, v49, s[0:1]
	ds_bpermute_b32 v53, v69, v53
	ds_read_b128 v[76:79], v65 offset:55312
	ds_read_b128 v[80:83], v65 offset:55296
	ds_read_b128 v[84:87], v65 offset:20496
	ds_read_b128 v[88:91], v65 offset:20480
	ds_read_b128 v[92:95], v65 offset:53264
	ds_read_b128 v[96:99], v65 offset:53248
	ds_read_b128 v[100:103], v65 offset:22544
	ds_read_b128 v[104:107], v65 offset:22528
	v_cndmask_b32_e64 v48, v49, v48, s[0:1]
	s_waitcnt lgkmcnt(4)
; __device__ __forceinline__ void phase0(const Params& P, unsigned char* smem) {
;     ...
; #pragma unroll
;             for (int i = 0; i < 8; ++i) {
;                 float dd[2];
; #pragma unroll
;                 for (int hh = 0; hh < 2; ++hh) {
;                     const float* gwc = gw + (i + 8 * hh) * 1024;
;                     const float4 w0 = *(const float4*)(gwc + c0), w1 = *(const float4*)(gwc + c0 + 4), w2 = *(const float4*)(gwc + c1), w3 = *(const float4*)(gwc + c1 + 4);
;                     dd[hh] = v[0] * w0.x + v[1] * w0.y + v[2] * w0.z + v[3] * w0.w + v[4] * w1.x + v[5] * w1.y + v[6] * w1.z + v[7] * w1.w
;                            + v[8] * w2.x + v[9] * w2.y + v[10] * w2.z + v[11] * w2.w + v[12] * w3.x + v[13] * w3.y + v[14] * w3.z + v[15] * w3.w;
;                 }
;                 const bool up = (lane & 32) != 0; const float keep = up ? dd[1] : dd[0], send = up ? dd[0] : dd[1];
;                 r8[i] = keep + __shfl_xor(send, 32, 64);
;                 if ((i & 3) == 3) __builtin_amdgcn_sched_barrier(0);
;             }
; #pragma unroll
;             for (int i = 0; i < 4; ++i) { const bool up = (lane & 16) != 0; const float keep = up ? r8[i + 4] : r8[i], send = up ? r8[i] : r8[i + 4]; r4[i] = keep + __shfl_xor(send, 16, 64); }
; #pragma unroll
;             for (int i = 0; i < 2; ++i) { const bool up = (lane & 8) != 0; const float keep = up ? r4[i + 2] : r4[i], send = up ? r4[i] : r4[i + 2]; r2[i] = keep + __shfl_xor(send, 8, 64); }
;             { const bool up = (lane & 4) != 0; const float keep = up ? r2[1] : r2[0], send = up ? r2[0] : r2[1]; r1 = keep + __shfl_xor(send, 4, 64); }
;             r1 += __shfl_xor(r1, 2, 64); r1 += __shfl_xor(r1, 1, 64);
	v_mul_f32_e32 v49, v62, v88
	v_fmac_f32_e32 v49, v63, v89
	v_add_f32_e32 v48, v48, v53
	s_waitcnt lgkmcnt(2)
	v_mul_f32_e32 v53, v62, v96
	v_fmac_f32_e32 v53, v63, v97
	v_fmac_f32_e32 v49, v60, v90
	v_fmac_f32_e32 v53, v60, v98
	v_fmac_f32_e32 v49, v61, v91
	v_fmac_f32_e32 v53, v61, v99
	v_fmac_f32_e32 v49, v58, v84
	v_fmac_f32_e32 v53, v58, v92
	v_fmac_f32_e32 v49, v59, v85
	v_fmac_f32_e32 v53, v59, v93
	v_fmac_f32_e32 v49, v46, v86
	v_fmac_f32_e32 v53, v46, v94
	v_fmac_f32_e32 v49, v47, v87
	v_fmac_f32_e32 v53, v47, v95
	s_waitcnt lgkmcnt(0)
	v_fmac_f32_e32 v49, v42, v104
	v_fmac_f32_e32 v53, v42, v80
	v_fmac_f32_e32 v49, v43, v105
	v_fmac_f32_e32 v53, v43, v81
	v_fmac_f32_e32 v49, v40, v106
	v_fmac_f32_e32 v53, v40, v82
	v_fmac_f32_e32 v49, v41, v107
	v_fmac_f32_e32 v53, v41, v83
	v_fmac_f32_e32 v49, v38, v100
	v_fmac_f32_e32 v53, v38, v76
	v_fmac_f32_e32 v49, v39, v101
	v_fmac_f32_e32 v53, v39, v77
	v_fmac_f32_e32 v49, v34, v102
	v_fmac_f32_e32 v53, v34, v78
	v_fmac_f32_e32 v49, v35, v103
	v_fmac_f32_e32 v53, v35, v79
	ds_read_b128 v[76:79], v65 offset:59408
	ds_read_b128 v[80:83], v65 offset:59392
	ds_read_b128 v[84:87], v65 offset:24592
	ds_read_b128 v[88:91], v65 offset:24576
	ds_read_b128 v[92:95], v65 offset:57360
	ds_read_b128 v[96:99], v65 offset:57344
	ds_read_b128 v[100:103], v65 offset:26640
	ds_read_b128 v[104:107], v65 offset:26624
	v_cndmask_b32_e64 v108, v53, v49, s[0:1]
	v_cndmask_b32_e64 v49, v49, v53, s[0:1]
	s_waitcnt lgkmcnt(4)
	v_mul_f32_e32 v53, v62, v88
	s_waitcnt lgkmcnt(2)
	v_mul_f32_e32 v109, v62, v96
	v_fmac_f32_e32 v53, v63, v89
	v_fmac_f32_e32 v109, v63, v97
	v_fmac_f32_e32 v53, v60, v90
	v_fmac_f32_e32 v109, v60, v98
	v_fmac_f32_e32 v53, v61, v91
	v_fmac_f32_e32 v109, v61, v99
	v_fmac_f32_e32 v53, v58, v84
	v_fmac_f32_e32 v109, v58, v92
	v_fmac_f32_e32 v53, v59, v85
	v_fmac_f32_e32 v109, v59, v93
	v_fmac_f32_e32 v53, v46, v86
	v_fmac_f32_e32 v109, v46, v94
	v_fmac_f32_e32 v53, v47, v87
	v_fmac_f32_e32 v109, v47, v95
	s_waitcnt lgkmcnt(0)
	v_fmac_f32_e32 v53, v42, v104
	v_fmac_f32_e32 v109, v42, v80
	v_fmac_f32_e32 v53, v43, v105
	v_fmac_f32_e32 v109, v43, v81
	v_fmac_f32_e32 v53, v40, v106
	v_fmac_f32_e32 v109, v40, v82
	v_fmac_f32_e32 v53, v41, v107
	v_fmac_f32_e32 v109, v41, v83
	v_fmac_f32_e32 v53, v38, v100
	v_fmac_f32_e32 v109, v38, v76
	v_fmac_f32_e32 v53, v39, v101
	v_fmac_f32_e32 v109, v39, v77
	v_fmac_f32_e32 v53, v34, v102
	v_fmac_f32_e32 v109, v34, v78
	v_fmac_f32_e32 v53, v35, v103
	v_fmac_f32_e32 v109, v35, v79
	v_cndmask_b32_e64 v76, v53, v109, s[0:1]
	ds_bpermute_b32 v110, v69, v76
	ds_read_b128 v[76:79], v65 offset:63504
	ds_read_b128 v[80:83], v65 offset:63488
	ds_read_b128 v[84:87], v65 offset:28688
	ds_read_b128 v[88:91], v65 offset:28672
	ds_read_b128 v[92:95], v65 offset:61456
	ds_read_b128 v[96:99], v65 offset:61440
	ds_read_b128 v[100:103], v65 offset:30736
	ds_read_b128 v[104:107], v65 offset:30720
	s_waitcnt lgkmcnt(4)
	v_mul_f32_e32 v88, v62, v88
	v_fmac_f32_e32 v88, v63, v89
	s_waitcnt lgkmcnt(2)
	v_mul_f32_e32 v62, v62, v96
	v_fmac_f32_e32 v62, v63, v97
	v_fmac_f32_e32 v88, v60, v90
	v_fmac_f32_e32 v62, v60, v98
	v_fmac_f32_e32 v88, v61, v91
	v_fmac_f32_e32 v62, v61, v99
	v_fmac_f32_e32 v88, v58, v84
	v_fmac_f32_e32 v62, v58, v92
	v_fmac_f32_e32 v88, v59, v85
	v_fmac_f32_e32 v62, v59, v93
	v_fmac_f32_e32 v88, v46, v86
	v_fmac_f32_e32 v62, v46, v94
	v_fmac_f32_e32 v88, v47, v87
	v_fmac_f32_e32 v62, v47, v95
	s_waitcnt lgkmcnt(0)
	v_fmac_f32_e32 v88, v42, v104
	v_fmac_f32_e32 v62, v42, v80
	v_fmac_f32_e32 v88, v43, v105
	v_fmac_f32_e32 v62, v43, v81
	v_fmac_f32_e32 v88, v40, v106
	v_fmac_f32_e32 v62, v40, v82
	v_fmac_f32_e32 v88, v41, v107
	v_fmac_f32_e32 v62, v41, v83
	v_fmac_f32_e32 v88, v38, v100
	v_fmac_f32_e32 v62, v38, v76
	v_fmac_f32_e32 v88, v39, v101
	v_fmac_f32_e32 v62, v39, v77
	v_fmac_f32_e32 v88, v34, v102
	v_fmac_f32_e32 v62, v34, v78
	v_fmac_f32_e32 v88, v35, v103
	v_fmac_f32_e32 v62, v35, v79
	v_cndmask_b32_e64 v34, v88, v62, s[0:1]
	ds_bpermute_b32 v49, v69, v49
	ds_bpermute_b32 v34, v69, v34
	v_cndmask_b32_e64 v39, v62, v88, s[0:1]
	v_cndmask_b32_e64 v38, v109, v53, s[0:1]
	v_add_f32_e32 v38, v38, v110
	s_waitcnt lgkmcnt(1)
	v_add_f32_e32 v35, v108, v49
	s_waitcnt lgkmcnt(0)
	v_add_f32_e32 v34, v39, v34
	s_waitcnt lgkmcnt(0)
	s_nop 0
	v_permlane16_swap_b32_e32 v36, v48
	v_permlane16_swap_b32_e32 v37, v35
	v_permlane16_swap_b32_e32 v44, v38
	v_permlane16_swap_b32_e32 v45, v34
	v_add_f32_e32 v36, v36, v48
	v_add_f32_e32 v35, v37, v35
	v_add_f32_e32 v37, v44, v38
	v_add_f32_e32 v34, v45, v34
	v_cndmask_b32_e64 v38, v36, v37, s[6:7]
	v_cndmask_b32_e64 v39, v35, v34, s[6:7]
	v_cndmask_b32_e64 v36, v37, v36, s[6:7]
	v_cndmask_b32_e64 v34, v34, v35, s[6:7]
	s_nop 0
	v_add_f32_dpp v36, v38, v36 row_ror:8 row_mask:0xf bank_mask:0xf
	v_add_f32_dpp v34, v39, v34 row_ror:8 row_mask:0xf bank_mask:0xf
	v_cndmask_b32_e64 v35, v36, v34, s[8:9]
	v_cndmask_b32_e64 v37, v34, v36, s[8:9]
	s_nop 1
	v_add_f32_dpp v34, v35, v37 row_shl:4 row_mask:0xf bank_mask:0x5
	v_add_f32_dpp v34, v35, v37 row_shr:4 row_mask:0xf bank_mask:0xa
	s_nop 1
	v_add_f32_dpp v34, v34, v34 quad_perm:[2,3,0,1] row_mask:0xf bank_mask:0xf
	s_nop 1
	v_add_f32_dpp v34, v34, v34 quad_perm:[1,0,3,2] row_mask:0xf bank_mask:0xf
	s_and_saveexec_b64 s[14:15], s[10:11]
	s_cbranch_execz .LBB0_32
; __device__ __forceinline__ float logsigmoidf(float x) { return fminf(x, 0.f) - log1pf(expf(-fabsf(x))); }
; __device__ __forceinline__ void phase0(const Params& P, unsigned char* smem) {
;     ...
;             r1 += __shfl_xor(r1, 2, 64); r1 += __shfl_xor(r1, 1, 64);
;             if ((lane & 3) == 0) {
;                 const float pre = r1 + mybias;
;                 gates[(size_t)r * 16 + myq] = myq < 4 ? pre : logsigmoidf(pre);
;             }
	v_add_f32_e32 v34, v64, v34
	s_and_saveexec_b64 s[62:63], vcc
	s_cbranch_execz .LBB0_31
	v_mul_f32_e64 v35, |v34|, s70
	v_rndne_f32_e32 v36, v35
	v_sub_f32_e32 v37, v35, v36
	v_fma_f32 v35, |v34|, s70, -v35
	v_fma_f32 v35, |v34|, s71, v35
	v_add_f32_e32 v35, v37, v35
	v_exp_f32_e32 v35, v35
	v_cvt_i32_f32_e32 v36, v36
	v_cmp_ngt_f32_e64 s[12:13], |v34|, s72
	v_max_f32_e32 v37, v34, v34
	v_min_f32_e32 v48, 0, v37
	v_ldexp_f32 v35, v35, v36
	v_cndmask_b32_e64 v35, 0, v35, s[12:13]
	v_cmp_nlt_f32_e64 s[12:13], |v34|, s73
	s_nop 1
	v_cndmask_b32_e64 v49, v68, v35, s[12:13]
	v_add_f32_e32 v36, 1.0, v49
	v_add_f32_e32 v34, -1.0, v36
	v_sub_f32_e32 v35, v34, v36
	v_add_f32_e32 v35, 1.0, v35
	v_sub_f32_e32 v34, v49, v34
	v_add_f32_e32 v37, v34, v35
	v_frexp_mant_f32_e32 v38, v36
	v_cvt_f64_f32_e32 v[34:35], v36
	v_frexp_exp_i32_f64_e32 v34, v[34:35]
	v_cmp_gt_f32_e64 s[12:13], s76, v38
	s_nop 1
	v_subbrev_co_u32_e64 v42, s[12:13], 0, v34, s[12:13]
	v_sub_u32_e32 v34, 0, v42
	v_ldexp_f32 v35, v36, v34
	v_add_f32_e32 v36, -1.0, v35
	v_add_f32_e32 v38, 1.0, v35
	v_ldexp_f32 v34, v37, v34
	v_add_f32_e32 v37, 1.0, v36
	v_add_f32_e32 v39, -1.0, v38
	v_sub_f32_e32 v37, v35, v37
	v_sub_f32_e32 v35, v35, v39
	v_add_f32_e32 v37, v34, v37
	v_add_f32_e32 v34, v34, v35
	v_add_f32_e32 v43, v38, v34
	v_rcp_f32_e32 v45, v43
	v_sub_f32_e32 v35, v38, v43
	v_add_f32_e32 v44, v34, v35
	v_add_f32_e32 v35, v36, v37
	v_mul_f32_e32 v47, v35, v45
	v_sub_f32_e32 v34, v36, v35
	v_mul_f32_e32 v36, v43, v47
	v_fma_f32 v38, v47, v43, -v36
	v_fmac_f32_e32 v38, v47, v44
	v_add_f32_e32 v46, v37, v34
	v_add_f32_e32 v34, v36, v38
	v_sub_f32_e32 v37, v35, v34
	v_pk_add_f32 v[40:41], v[34:35], v[36:37] neg_lo:[0,1] neg_hi:[0,1]
	v_mov_b32_e32 v39, v34
	v_pk_add_f32 v[34:35], v[40:41], v[38:39] neg_lo:[0,1] neg_hi:[0,1]
	v_cmp_neq_f32_e64 s[12:13], s75, v49
	v_add_f32_e32 v35, v46, v35
	v_add_f32_e32 v34, v34, v35
	v_add_f32_e32 v35, v37, v34
	v_mul_f32_e32 v46, v45, v35
	v_mul_f32_e32 v36, v43, v46
	v_fma_f32 v38, v46, v43, -v36
	v_fmac_f32_e32 v38, v46, v44
	v_sub_f32_e32 v37, v37, v35
	v_add_f32_e32 v43, v34, v37
	v_add_f32_e32 v34, v36, v38
	v_sub_f32_e32 v37, v35, v34
	v_pk_add_f32 v[40:41], v[34:35], v[36:37] neg_lo:[0,1] neg_hi:[0,1]
	v_mov_b32_e32 v39, v34
	v_pk_add_f32 v[34:35], v[40:41], v[38:39] neg_lo:[0,1] neg_hi:[0,1]
	s_nop 0
	v_add_f32_e32 v35, v43, v35
	v_add_f32_e32 v34, v34, v35
	v_add_f32_e32 v35, v47, v46
	v_add_f32_e32 v34, v37, v34
	v_sub_f32_e32 v36, v35, v47
	v_mul_f32_e32 v34, v45, v34
	v_sub_f32_e32 v36, v46, v36
	v_add_f32_e32 v36, v36, v34
	v_add_f32_e32 v38, v35, v36
	v_mul_f32_e32 v39, v38, v38
	v_fmamk_f32 v34, v39, 0x3e9b6dac, v67
	v_fmaak_f32 v53, v39, v34, 0x3f2aaada
	v_cvt_f32_i32_e32 v34, v42
	v_sub_f32_e32 v35, v38, v35
	v_sub_f32_e32 v35, v36, v35
	v_ldexp_f32 v40, v35, 1
	v_mul_f32_e32 v35, v38, v39
	v_ldexp_f32 v37, v38, 1
	v_pk_mul_f32 v[38:39], v[34:35], v[52:53]
	s_nop 0
	v_fma_f32 v36, v34, s77, -v38
	v_fmac_f32_e32 v36, 0xb102e308, v34
	v_pk_add_f32 v[34:35], v[38:39], v[36:37]
	s_nop 0
	v_sub_f32_e32 v37, v35, v37
	v_sub_f32_e32 v37, v39, v37
	v_add_f32_e32 v41, v40, v37
	v_mov_b32_e32 v40, v38
	v_pk_add_f32 v[38:39], v[34:35], v[38:39] neg_lo:[0,1] neg_hi:[0,1]
	v_pk_add_f32 v[42:43], v[34:35], v[40:41]
	v_mov_b32_e32 v37, v34
	v_mov_b32_e32 v39, v43
	v_pk_add_f32 v[44:45], v[36:37], v[38:39] neg_lo:[0,1] neg_hi:[0,1]
	v_pk_add_f32 v[36:37], v[36:37], v[38:39]
	v_mov_b32_e32 v40, v41
	v_pk_add_f32 v[38:39], v[36:37], v[34:35] op_sel:[1,0] op_sel_hi:[0,1] neg_lo:[0,1] neg_hi:[0,1]
	v_pk_add_f32 v[46:47], v[42:43], v[38:39] op_sel_hi:[1,0] neg_lo:[0,1] neg_hi:[0,1]
	v_mov_b32_e32 v42, v43
	v_mov_b32_e32 v43, v37
	v_pk_mov_b32 v[38:39], v[34:35], v[38:39] op_sel:[1,0]
	v_mov_b32_e32 v41, v34
	v_pk_add_f32 v[38:39], v[42:43], v[38:39] neg_lo:[0,1] neg_hi:[0,1]
	v_mov_b32_e32 v46, v44
	v_pk_add_f32 v[34:35], v[40:41], v[38:39] neg_lo:[0,1] neg_hi:[0,1]
	v_mov_b32_e32 v45, v37
	v_pk_add_f32 v[38:39], v[46:47], v[34:35]
	s_nop 0
	v_pk_add_f32 v[40:41], v[38:39], v[38:39] op_sel:[0,1] op_sel_hi:[1,0]
	s_nop 0
	v_pk_add_f32 v[36:37], v[36:37], v[40:41] op_sel:[1,0] op_sel_hi:[0,1]
	v_mov_b32_e32 v39, v36
	v_pk_add_f32 v[42:43], v[38:39], v[44:45] neg_lo:[0,1] neg_hi:[0,1]
	v_mov_b32_e32 v35, v40
	v_sub_f32_e32 v37, v38, v42
	v_pk_add_f32 v[34:35], v[34:35], v[42:43] neg_lo:[0,1] neg_hi:[0,1]
	v_sub_f32_e32 v37, v44, v37
	v_add_f32_e32 v34, v34, v37
	v_add_f32_e32 v34, v34, v35
	v_add_f32_e32 v34, v36, v34
	v_cndmask_b32_e64 v34, v68, v34, s[12:13]
	v_cmp_lt_f32_e64 s[12:13], |v49|, s78
	s_nop 1
	v_cndmask_b32_e64 v34, v34, v49, s[12:13]
	v_sub_f32_e32 v34, v48, v34
	s_branch .LBB0_31
